# negc refresh in attention kv loops: 16 uniform v_cndmask per step replaced by a scalar branch around 16 v_mov (6 sites)
# speedup vs baseline: 1.0119x; 1.0071x over previous
.LBB0_733:
	s_add_i32 s16, s16, 2
	v_cmp_neq_f32_e64 s[0:1], -v220, v191
	s_cmp_eq_u64 s[0:1], 0
	v_sub_f32_e32 v192, 0, v220
	s_cselect_b64 s[48:49], -1, 0
	v_mov_b32_e32 v190, 0
	s_cmp_lg_u64 s[48:49], 0
	s_cbranch_scc1 .Lnegc_keep_0
	v_mov_b32_e32 v129, v192
	v_mov_b32_e32 v128, v192
	v_mov_b32_e32 v127, v192
	v_mov_b32_e32 v126, v192
	v_mov_b32_e32 v125, v192
	v_mov_b32_e32 v124, v192
	v_mov_b32_e32 v123, v192
	v_mov_b32_e32 v122, v192
	v_mov_b32_e32 v121, v192
	v_mov_b32_e32 v120, v192
	v_mov_b32_e32 v119, v192
	v_mov_b32_e32 v118, v192
	v_mov_b32_e32 v117, v192
	v_mov_b32_e32 v116, v192
	v_mov_b32_e32 v115, v192
	v_mov_b32_e32 v114, v192
.Lnegc_keep_0:
	s_min_u32 s4, s16, 29
	s_add_i32 s6, s4, 2
	v_mad_u64_u32 v[66:67], s[0:1], v194, s6, v[206:207]
	global_load_dwordx4 v[162:165], v[66:67], off
	v_mad_u64_u32 v[66:67], s[0:1], v208, s6, v[210:211]
	global_load_dwordx4 v[158:161], v[66:67], off
	global_load_dwordx4 v[154:157], v[214:215], off
	ds_read_b128 v[66:69], v219 offset:13312
	ds_read_b128 v[174:177], v219 offset:13344
	ds_read_b128 v[86:89], v219 offset:19968
	ds_read_b128 v[186:189], v219 offset:13376
	ds_read_b128 v[178:181], v219 offset:20000
	ds_read_b128 v[182:185], v219 offset:20032
	v_max3_f32 v0, v240, v50, v51
	v_max3_f32 v70, v240, v52, v53
	s_nop 0
	v_max3_f32 v0, v0, v34, v35
	v_max3_f32 v70, v70, v36, v37
	s_waitcnt lgkmcnt(5)
	v_mfma_f32_32x32x16_bf16 v[98:113], v[66:69], v[130:133], v[114:129]
	ds_read_b128 v[94:97], v219 offset:13408
	ds_read_b128 v[82:85], v219 offset:20064
	v_max3_f32 v0, v0, v54, v55
	v_max3_f32 v70, v70, v56, v57
	s_nop 0
	v_max3_f32 v0, v0, v38, v39
	v_max3_f32 v70, v70, v40, v41
	s_nop 0
	v_max3_f32 v66, v70, v60, v61
	v_max3_f32 v0, v0, v58, v59
	s_nop 0
	v_max3_f32 v193, v66, v44, v45
	s_waitcnt lgkmcnt(5)
	v_mfma_f32_32x32x16_bf16 v[66:81], v[86:89], v[130:133], v[114:129]
	v_max3_f32 v0, v0, v42, v43
	ds_read_b128 v[90:93], v219 offset:13440
	ds_read_b128 v[86:89], v219 offset:20096
	ds_read_b64_tr_b16 v[170:171], v221 offset:26624
	ds_read_b64_tr_b16 v[172:173], v221 offset:27136
	ds_read_b64_tr_b16 v[166:167], v221 offset:30720
	ds_read_b64_tr_b16 v[168:169], v221 offset:31232
	v_mfma_f32_32x32x16_bf16 v[98:113], v[174:177], v[134:137], v[98:113]
	v_max3_f32 v0, v0, v62, v63
	v_max3_f32 v174, v193, v64, v65
	s_nop 0
	v_max3_f32 v0, v0, v46, v47
	v_max3_f32 v174, v174, v48, v49
	s_waitcnt lgkmcnt(9)
	v_mfma_f32_32x32x16_bf16 v[66:81], v[178:181], v[134:137], v[66:81]
	v_max_f32_e32 v0, v0, v174
	s_nop 0
	v_mov_b32_e32 v174, v0
	s_nop 1
	v_permlane32_swap_b32_e32 v0, v174
	v_max_f32_e32 v0, v0, v174
	s_nop 0
	v_cmp_lt_f32_e32 vcc, s2, v0
	v_cmp_gt_f32_e64 s[0:1], s3, v0
	s_or_b64 vcc, vcc, s[0:1]
	v_cndmask_b32_e64 v174, 0, 1, vcc
	v_cmp_ne_u32_e64 s[50:51], 0, v174
	s_cmp_lg_u64 s[50:51], 0
	s_cselect_b64 s[14:15], -1, 0
	s_cbranch_vccz .LBB0_735
	v_cmp_lt_f32_e32 vcc, 0, v0
	s_or_b64 vcc, vcc, s[0:1]
	s_nop 0
	v_cndmask_b32_e32 v190, 0, v0, vcc
	v_exp_f32_e64 v0, -v190
	v_pk_add_f32 v[50:51], v[50:51], v[190:191] op_sel_hi:[1,0] neg_lo:[0,1] neg_hi:[0,1]
	v_pk_add_f32 v[52:53], v[52:53], v[190:191] op_sel_hi:[1,0] neg_lo:[0,1] neg_hi:[0,1]
	v_pk_add_f32 v[54:55], v[54:55], v[190:191] op_sel_hi:[1,0] neg_lo:[0,1] neg_hi:[0,1]
	v_pk_add_f32 v[56:57], v[56:57], v[190:191] op_sel_hi:[1,0] neg_lo:[0,1] neg_hi:[0,1]
	v_pk_add_f32 v[58:59], v[58:59], v[190:191] op_sel_hi:[1,0] neg_lo:[0,1] neg_hi:[0,1]
	v_pk_add_f32 v[60:61], v[60:61], v[190:191] op_sel_hi:[1,0] neg_lo:[0,1] neg_hi:[0,1]
	v_pk_add_f32 v[62:63], v[62:63], v[190:191] op_sel_hi:[1,0] neg_lo:[0,1] neg_hi:[0,1]
	v_pk_add_f32 v[64:65], v[64:65], v[190:191] op_sel_hi:[1,0] neg_lo:[0,1] neg_hi:[0,1]
	v_sub_f32_e32 v49, v49, v190
	v_sub_f32_e32 v48, v48, v190
	v_sub_f32_e32 v47, v47, v190
	v_sub_f32_e32 v46, v46, v190
	v_sub_f32_e32 v45, v45, v190
	v_sub_f32_e32 v44, v44, v190
	v_sub_f32_e32 v43, v43, v190
	v_sub_f32_e32 v42, v42, v190
	v_sub_f32_e32 v41, v41, v190
	v_sub_f32_e32 v40, v40, v190
	v_sub_f32_e32 v39, v39, v190
	v_sub_f32_e32 v38, v38, v190
	v_sub_f32_e32 v37, v37, v190
	v_sub_f32_e32 v36, v36, v190
	v_sub_f32_e32 v35, v35, v190
	v_sub_f32_e32 v34, v34, v190
	v_add_f32_e32 v220, v220, v190
	s_branch .LBB0_736

.LBB0_744:
	v_cndmask_b32_e64 v83, v192, v191, s[48:49]
	v_cmp_neq_f32_e64 s[0:1], -v220, v83
	s_cmp_eq_u64 s[0:1], 0
	v_sub_f32_e32 v223, 0, v220
	s_cselect_b64 s[48:49], -1, 0
	v_mov_b32_e32 v216, 0
	s_cmp_lg_u64 s[48:49], 0
	s_cbranch_scc1 .Lnegc_keep_1
	v_mov_b32_e32 v129, v223
	v_mov_b32_e32 v128, v223
	v_mov_b32_e32 v127, v223
	v_mov_b32_e32 v126, v223
	v_mov_b32_e32 v125, v223
	v_mov_b32_e32 v124, v223
	v_mov_b32_e32 v123, v223
	v_mov_b32_e32 v122, v223
	v_mov_b32_e32 v121, v223
	v_mov_b32_e32 v120, v223
	v_mov_b32_e32 v119, v223
	v_mov_b32_e32 v118, v223
	v_mov_b32_e32 v117, v223
	v_mov_b32_e32 v116, v223
	v_mov_b32_e32 v115, v223
	v_mov_b32_e32 v114, v223
.Lnegc_keep_1:
	s_min_u32 s0, s16, 28
	s_add_i32 s6, s0, 3
	v_mad_u64_u32 v[34:35], s[0:1], v194, s6, v[206:207]
	global_load_dwordx4 v[162:165], v[34:35], off
	v_mad_u64_u32 v[34:35], s[0:1], v208, s6, v[210:211]
	s_lshl_b32 s40, s4, 18
	global_load_dwordx4 v[158:161], v[34:35], off
	v_lshl_add_u64 v[34:35], v[212:213], 0, s[40:41]
	s_mov_b32 s0, 0x80000
	v_add_co_u32_e32 v34, vcc, s0, v34
	v_max3_f32 v38, v240, v98, v99
	v_max3_f32 v39, v240, v100, v101
	s_nop 1
	v_addc_co_u32_e32 v35, vcc, 0, v35, vcc
	global_load_dwordx4 v[154:157], v[34:35], off offset:128
	ds_read_b128 v[34:37], v219
	ds_read_b128 v[174:177], v219 offset:32
	ds_read_b128 v[88:91], v219 offset:6656
	ds_read_b128 v[190:193], v219 offset:64
	ds_read_b128 v[178:181], v219 offset:6688
	ds_read_b128 v[186:189], v219 offset:6720
	v_max3_f32 v38, v38, v66, v67
	v_max3_f32 v39, v39, v68, v69
	s_waitcnt lgkmcnt(5)
	v_mfma_f32_32x32x16_bf16 v[50:65], v[34:37], v[130:133], v[114:129]
	ds_read_b128 v[182:185], v219 offset:96
	ds_read_b128 v[84:87], v219 offset:6752
	v_max3_f32 v38, v38, v102, v103
	v_max3_f32 v39, v39, v104, v105
	s_nop 0
	v_max3_f32 v38, v38, v70, v71
	v_max3_f32 v39, v39, v72, v73
	s_nop 0
	v_max3_f32 v34, v38, v106, v107
	v_max3_f32 v35, v39, v108, v109
	s_nop 0
	v_max3_f32 v96, v34, v74, v75
	v_max3_f32 v97, v35, v76, v77
	s_waitcnt lgkmcnt(5)
	v_mfma_f32_32x32x16_bf16 v[34:49], v[88:91], v[130:133], v[114:129]
	ds_read_b128 v[92:95], v219 offset:128
	ds_read_b128 v[88:91], v219 offset:6784
	ds_read_b64_tr_b16 v[170:171], v221 offset:34816
	ds_read_b64_tr_b16 v[172:173], v221 offset:35328
	ds_read_b64_tr_b16 v[166:167], v221 offset:38912
	ds_read_b64_tr_b16 v[168:169], v221 offset:39424
	v_mfma_f32_32x32x16_bf16 v[50:65], v[174:177], v[134:137], v[50:65]
	v_max3_f32 v96, v96, v110, v111
	v_max3_f32 v97, v97, v112, v113
	s_nop 0
	v_max3_f32 v96, v96, v78, v79
	v_max3_f32 v97, v97, v80, v81
	s_waitcnt lgkmcnt(9)
	v_mfma_f32_32x32x16_bf16 v[34:49], v[178:181], v[134:137], v[34:49]
	v_max_f32_e32 v96, v96, v97
	s_nop 0
	v_mov_b32_e32 v97, v96
	s_nop 1
	v_permlane32_swap_b32_e32 v96, v97
	v_max_f32_e32 v96, v96, v97
	s_nop 0
	v_cmp_lt_f32_e32 vcc, s2, v96
	v_cmp_gt_f32_e64 s[0:1], s3, v96
	s_or_b64 vcc, vcc, s[0:1]
	v_cndmask_b32_e64 v97, 0, 1, vcc
	v_cmp_ne_u32_e64 s[50:51], 0, v97
	s_cmp_lg_u64 s[50:51], 0
	s_cselect_b64 s[14:15], -1, 0
	s_cbranch_vccz .LBB0_746
	v_cmp_lt_f32_e32 vcc, 0, v96
	s_or_b64 vcc, vcc, s[0:1]
	s_nop 0
	v_cndmask_b32_e32 v216, 0, v96, vcc
	v_exp_f32_e64 v218, -v216
	v_pk_add_f32 v[98:99], v[98:99], v[216:217] op_sel_hi:[1,0] neg_lo:[0,1] neg_hi:[0,1]
	v_pk_add_f32 v[100:101], v[100:101], v[216:217] op_sel_hi:[1,0] neg_lo:[0,1] neg_hi:[0,1]
	v_pk_add_f32 v[102:103], v[102:103], v[216:217] op_sel_hi:[1,0] neg_lo:[0,1] neg_hi:[0,1]
	v_pk_add_f32 v[104:105], v[104:105], v[216:217] op_sel_hi:[1,0] neg_lo:[0,1] neg_hi:[0,1]
	v_pk_add_f32 v[106:107], v[106:107], v[216:217] op_sel_hi:[1,0] neg_lo:[0,1] neg_hi:[0,1]
	v_pk_add_f32 v[108:109], v[108:109], v[216:217] op_sel_hi:[1,0] neg_lo:[0,1] neg_hi:[0,1]
	v_pk_add_f32 v[110:111], v[110:111], v[216:217] op_sel_hi:[1,0] neg_lo:[0,1] neg_hi:[0,1]
	v_pk_add_f32 v[112:113], v[112:113], v[216:217] op_sel_hi:[1,0] neg_lo:[0,1] neg_hi:[0,1]
	v_sub_f32_e32 v81, v81, v216
	v_sub_f32_e32 v80, v80, v216
	v_sub_f32_e32 v79, v79, v216
	v_sub_f32_e32 v78, v78, v216
	v_sub_f32_e32 v77, v77, v216
	v_sub_f32_e32 v76, v76, v216
	v_sub_f32_e32 v75, v75, v216
	v_sub_f32_e32 v74, v74, v216
	v_sub_f32_e32 v73, v73, v216
	v_sub_f32_e32 v72, v72, v216
	v_sub_f32_e32 v71, v71, v216
	v_sub_f32_e32 v70, v70, v216
	v_sub_f32_e32 v69, v69, v216
	v_sub_f32_e32 v68, v68, v216
	v_sub_f32_e32 v67, v67, v216
	v_sub_f32_e32 v66, v66, v216
	v_add_f32_e32 v220, v220, v216
	s_branch .LBB0_747

.LBB0_929:
	s_waitcnt lgkmcnt(0)
	v_sub_f32_e32 v218, v0, v217
	s_add_i32 s34, s4, 2
	v_cmp_neq_f32_e32 vcc, v218, v112
	s_cmp_eq_u64 vcc, 0
	s_cselect_b64 s[46:47], -1, 0
	s_cmp_lg_u64 s[46:47], 0
	s_cbranch_scc1 .Lnegc_keep_2
	v_mov_b32_e32 v175, v218
	v_mov_b32_e32 v174, v218
	v_mov_b32_e32 v173, v218
	v_mov_b32_e32 v172, v218
	v_mov_b32_e32 v171, v218
	v_mov_b32_e32 v170, v218
	v_mov_b32_e32 v169, v218
	v_mov_b32_e32 v168, v218
	v_mov_b32_e32 v167, v218
	v_mov_b32_e32 v166, v218
	v_mov_b32_e32 v165, v218
	v_mov_b32_e32 v164, v218
	v_mov_b32_e32 v163, v218
	v_mov_b32_e32 v162, v218
	v_mov_b32_e32 v161, v218
	v_mov_b32_e32 v160, v218
.Lnegc_keep_2:
	s_min_u32 s0, s34, 29
	s_add_i32 s0, s0, 2
	v_mul_u32_u24_e32 v0, s0, v206
	v_add_co_u32_e32 v10, vcc, s93, v212
	v_lshl_add_u64 v[2:3], v[208:209], 0, v[0:1]
	s_nop 0
	v_addc_co_u32_e32 v11, vcc, 0, v213, vcc
	global_load_dwordx4 v[2:5], v[2:3], off
	s_nop 0
	global_load_dwordx4 v[6:9], v[212:213], off
	s_nop 0
	global_load_dwordx4 v[10:13], v[10:11], off
	ds_read_b128 v[96:99], v215 offset:9216
	ds_read_b128 v[220:223], v215 offset:9248
	ds_read_b128 v[114:117], v215 offset:13824
	ds_read_b128 v[224:227], v215 offset:13856
	v_max3_f32 v0, v240, v128, v129
	v_max3_f32 v14, v240, v130, v131
	s_nop 0
	v_max3_f32 v0, v0, v80, v81
	v_max3_f32 v14, v14, v82, v83
	s_waitcnt lgkmcnt(3)
	v_mfma_f32_32x32x16_bf16 v[144:159], v[96:99], v[176:179], v[160:175]
	ds_read_b128 v[192:195], v215 offset:9280
	ds_read_b128 v[118:121], v215 offset:13888
	v_max3_f32 v0, v0, v132, v133
	v_max3_f32 v14, v14, v134, v135
	s_nop 0
	v_max3_f32 v0, v0, v84, v85
	v_max3_f32 v14, v14, v86, v87
	s_waitcnt lgkmcnt(3)
	v_mfma_f32_32x32x16_bf16 v[96:111], v[114:117], v[176:179], v[160:175]
	v_max3_f32 v0, v0, v136, v137
	v_max3_f32 v14, v14, v138, v139
	s_nop 0
	v_max3_f32 v0, v0, v88, v89
	v_max3_f32 v14, v14, v90, v91
	v_mfma_f32_32x32x16_bf16 v[144:159], v[220:223], v[180:183], v[144:159]
	ds_read_b128 v[122:125], v215 offset:9312
	ds_read_b128 v[114:117], v215 offset:13920
	v_max3_f32 v0, v0, v140, v141
	v_max3_f32 v14, v14, v142, v143
	s_nop 0
	v_max3_f32 v0, v0, v92, v93
	v_max3_f32 v14, v14, v94, v95
	s_waitcnt lgkmcnt(4)
	v_mfma_f32_32x32x16_bf16 v[96:111], v[224:227], v[180:183], v[96:111]
	v_max_f32_e32 v0, v0, v14
	s_nop 0
	v_mov_b32_e32 v14, v0
	s_nop 1
	v_permlane32_swap_b32_e32 v0, v14
	v_max_f32_e32 v0, v0, v14
	s_nop 0
	v_cmp_lt_f32_e32 vcc, s2, v0
	v_cmp_gt_f32_e64 s[0:1], s3, v0
	s_or_b64 vcc, vcc, s[0:1]
	v_cndmask_b32_e64 v14, 0, 1, vcc
	v_cmp_ne_u32_e64 s[48:49], 0, v14
	s_cmp_lg_u64 s[48:49], 0
	s_cselect_b64 s[20:21], -1, 0
	s_cbranch_vccz .LBB0_931
	v_cmp_lt_f32_e32 vcc, 0, v0
	s_or_b64 vcc, vcc, s[0:1]
	s_nop 0
	v_cndmask_b32_e32 v0, 0, v0, vcc
	v_exp_f32_e64 v14, -v0
	v_pk_add_f32 v[128:129], v[128:129], v[0:1] op_sel_hi:[1,0] neg_lo:[0,1] neg_hi:[0,1]
	v_pk_add_f32 v[130:131], v[130:131], v[0:1] op_sel_hi:[1,0] neg_lo:[0,1] neg_hi:[0,1]
	v_pk_add_f32 v[132:133], v[132:133], v[0:1] op_sel_hi:[1,0] neg_lo:[0,1] neg_hi:[0,1]
	v_pk_add_f32 v[134:135], v[134:135], v[0:1] op_sel_hi:[1,0] neg_lo:[0,1] neg_hi:[0,1]
	v_pk_add_f32 v[136:137], v[136:137], v[0:1] op_sel_hi:[1,0] neg_lo:[0,1] neg_hi:[0,1]
	v_pk_add_f32 v[138:139], v[138:139], v[0:1] op_sel_hi:[1,0] neg_lo:[0,1] neg_hi:[0,1]
	v_pk_add_f32 v[140:141], v[140:141], v[0:1] op_sel_hi:[1,0] neg_lo:[0,1] neg_hi:[0,1]
	v_pk_add_f32 v[142:143], v[142:143], v[0:1] op_sel_hi:[1,0] neg_lo:[0,1] neg_hi:[0,1]
	v_sub_f32_e32 v95, v95, v0
	v_sub_f32_e32 v94, v94, v0
	v_sub_f32_e32 v93, v93, v0
	v_sub_f32_e32 v92, v92, v0
	v_sub_f32_e32 v91, v91, v0
	v_sub_f32_e32 v90, v90, v0
	v_sub_f32_e32 v89, v89, v0
	v_sub_f32_e32 v88, v88, v0
	v_sub_f32_e32 v87, v87, v0
	v_sub_f32_e32 v86, v86, v0
	v_sub_f32_e32 v85, v85, v0
	v_sub_f32_e32 v84, v84, v0
	v_sub_f32_e32 v83, v83, v0
	v_sub_f32_e32 v82, v82, v0
	v_sub_f32_e32 v81, v81, v0
	v_sub_f32_e32 v80, v80, v0
	v_add_f32_e32 v217, v217, v0
	s_branch .LBB0_932

.LBB0_946:
	v_cndmask_b32_e64 v115, v218, v112, s[46:47]
	s_waitcnt lgkmcnt(0)
	v_sub_f32_e32 v218, v0, v217
	s_add_i32 s0, s4, 4
	v_cmp_neq_f32_e32 vcc, v218, v115
	s_cmp_eq_u64 vcc, 0
	s_cselect_b64 s[46:47], -1, 0
	s_cmp_lg_u64 s[46:47], 0
	s_cbranch_scc1 .Lnegc_keep_3
	v_mov_b32_e32 v175, v218
	v_mov_b32_e32 v174, v218
	v_mov_b32_e32 v173, v218
	v_mov_b32_e32 v172, v218
	v_mov_b32_e32 v171, v218
	v_mov_b32_e32 v170, v218
	v_mov_b32_e32 v169, v218
	v_mov_b32_e32 v168, v218
	v_mov_b32_e32 v167, v218
	v_mov_b32_e32 v166, v218
	v_mov_b32_e32 v165, v218
	v_mov_b32_e32 v164, v218
	v_mov_b32_e32 v163, v218
	v_mov_b32_e32 v162, v218
	v_mov_b32_e32 v161, v218
	v_mov_b32_e32 v160, v218
.Lnegc_keep_3:
	s_min_u32 s0, s0, 31
	s_min_u32 s1, s34, 28
	s_mul_i32 s40, s0, 0x108000
	s_add_i32 s1, s1, 3
	v_lshl_add_u64 v[6:7], v[210:211], 0, s[40:41]
	v_mul_u32_u24_e32 v0, s1, v206
	v_add_co_u32_e32 v10, vcc, s93, v6
	v_lshl_add_u64 v[2:3], v[208:209], 0, v[0:1]
	s_nop 0
	v_addc_co_u32_e32 v11, vcc, 0, v7, vcc
	global_load_dwordx4 v[2:5], v[2:3], off
	s_nop 0
	global_load_dwordx4 v[6:9], v[6:7], off
	s_nop 0
	global_load_dwordx4 v[10:13], v[10:11], off
	ds_read_b128 v[80:83], v215
	ds_read_b128 v[196:199], v215 offset:32
	ds_read_b128 v[116:119], v215 offset:4608
	ds_read_b128 v[200:203], v215 offset:4640
	v_max3_f32 v0, v240, v144, v145
	v_max3_f32 v84, v240, v146, v147
	s_nop 0
	v_max3_f32 v0, v0, v96, v97
	v_max3_f32 v84, v84, v98, v99
	s_waitcnt lgkmcnt(3)
	v_mfma_f32_32x32x16_bf16 v[128:143], v[80:83], v[176:179], v[160:175]
	ds_read_b128 v[192:195], v215 offset:64
	ds_read_b128 v[120:123], v215 offset:4672
	v_max3_f32 v0, v0, v148, v149
	v_max3_f32 v84, v84, v150, v151
	s_nop 0
	v_max3_f32 v0, v0, v100, v101
	v_max3_f32 v84, v84, v102, v103
	s_nop 0
	v_max3_f32 v80, v84, v154, v155
	v_max3_f32 v0, v0, v152, v153
	s_nop 0
	v_max3_f32 v112, v80, v106, v107
	s_waitcnt lgkmcnt(3)
	v_mfma_f32_32x32x16_bf16 v[80:95], v[116:119], v[176:179], v[160:175]
	v_max3_f32 v0, v0, v104, v105
	v_mfma_f32_32x32x16_bf16 v[128:143], v[196:199], v[180:183], v[128:143]
	ds_read_b128 v[124:127], v215 offset:96
	ds_read_b128 v[116:119], v215 offset:4704
	v_max3_f32 v0, v0, v156, v157
	v_max3_f32 v112, v112, v158, v159
	s_nop 0
	v_max3_f32 v0, v0, v108, v109
	v_max3_f32 v112, v112, v110, v111
	s_waitcnt lgkmcnt(4)
	v_mfma_f32_32x32x16_bf16 v[80:95], v[200:203], v[180:183], v[80:95]
	v_max_f32_e32 v0, v0, v112
	s_nop 0
	v_mov_b32_e32 v112, v0
	s_nop 1
	v_permlane32_swap_b32_e32 v0, v112
	v_max_f32_e32 v0, v0, v112
	s_nop 0
	v_cmp_lt_f32_e32 vcc, s2, v0
	v_cmp_gt_f32_e64 s[0:1], s3, v0
	s_or_b64 vcc, vcc, s[0:1]
	v_cndmask_b32_e64 v112, 0, 1, vcc
	v_cmp_ne_u32_e64 s[48:49], 0, v112
	s_cmp_lg_u64 s[48:49], 0
	s_cselect_b64 s[20:21], -1, 0
	s_cbranch_vccz .LBB0_948
	v_cmp_lt_f32_e32 vcc, 0, v0
	s_or_b64 vcc, vcc, s[0:1]
	s_nop 0
	v_cndmask_b32_e32 v0, 0, v0, vcc
	v_exp_f32_e64 v112, -v0
	v_pk_add_f32 v[144:145], v[144:145], v[0:1] op_sel_hi:[1,0] neg_lo:[0,1] neg_hi:[0,1]
	v_pk_add_f32 v[146:147], v[146:147], v[0:1] op_sel_hi:[1,0] neg_lo:[0,1] neg_hi:[0,1]
	v_pk_add_f32 v[148:149], v[148:149], v[0:1] op_sel_hi:[1,0] neg_lo:[0,1] neg_hi:[0,1]
	v_pk_add_f32 v[150:151], v[150:151], v[0:1] op_sel_hi:[1,0] neg_lo:[0,1] neg_hi:[0,1]
	v_pk_add_f32 v[152:153], v[152:153], v[0:1] op_sel_hi:[1,0] neg_lo:[0,1] neg_hi:[0,1]
	v_pk_add_f32 v[154:155], v[154:155], v[0:1] op_sel_hi:[1,0] neg_lo:[0,1] neg_hi:[0,1]
	v_pk_add_f32 v[156:157], v[156:157], v[0:1] op_sel_hi:[1,0] neg_lo:[0,1] neg_hi:[0,1]
	v_pk_add_f32 v[158:159], v[158:159], v[0:1] op_sel_hi:[1,0] neg_lo:[0,1] neg_hi:[0,1]
	v_sub_f32_e32 v111, v111, v0
	v_sub_f32_e32 v110, v110, v0
	v_sub_f32_e32 v109, v109, v0
	v_sub_f32_e32 v108, v108, v0
	v_sub_f32_e32 v107, v107, v0
	v_sub_f32_e32 v106, v106, v0
	v_sub_f32_e32 v105, v105, v0
	v_sub_f32_e32 v104, v104, v0
	v_sub_f32_e32 v103, v103, v0
	v_sub_f32_e32 v102, v102, v0
	v_sub_f32_e32 v101, v101, v0
	v_sub_f32_e32 v100, v100, v0
	v_sub_f32_e32 v99, v99, v0
	v_sub_f32_e32 v98, v98, v0
	v_sub_f32_e32 v97, v97, v0
	v_sub_f32_e32 v96, v96, v0
	v_add_f32_e32 v217, v217, v0
	s_branch .LBB0_949

.LBB0_975:
	s_waitcnt lgkmcnt(0)
	v_sub_f32_e32 v218, v0, v217
	s_add_i32 s17, s4, 2
	v_cmp_neq_f32_e32 vcc, v218, v112
	s_cmp_eq_u64 vcc, 0
	s_cselect_b64 s[46:47], -1, 0
	s_cmp_lg_u64 s[46:47], 0
	s_cbranch_scc1 .Lnegc_keep_4
	v_mov_b32_e32 v175, v218
	v_mov_b32_e32 v174, v218
	v_mov_b32_e32 v173, v218
	v_mov_b32_e32 v172, v218
	v_mov_b32_e32 v171, v218
	v_mov_b32_e32 v170, v218
	v_mov_b32_e32 v169, v218
	v_mov_b32_e32 v168, v218
	v_mov_b32_e32 v167, v218
	v_mov_b32_e32 v166, v218
	v_mov_b32_e32 v165, v218
	v_mov_b32_e32 v164, v218
	v_mov_b32_e32 v163, v218
	v_mov_b32_e32 v162, v218
	v_mov_b32_e32 v161, v218
	v_mov_b32_e32 v160, v218
.Lnegc_keep_4:
	s_min_u32 s0, s17, 29
	s_add_i32 s0, s0, 2
	v_mul_u32_u24_e32 v0, s0, v206
	v_add_co_u32_e32 v10, vcc, s93, v212
	v_lshl_add_u64 v[2:3], v[208:209], 0, v[0:1]
	s_nop 0
	v_addc_co_u32_e32 v11, vcc, 0, v213, vcc
	global_load_dwordx4 v[2:5], v[2:3], off
	s_nop 0
	global_load_dwordx4 v[6:9], v[212:213], off
	s_nop 0
	global_load_dwordx4 v[10:13], v[10:11], off
	ds_read_b128 v[96:99], v215 offset:9216
	ds_read_b128 v[196:199], v215 offset:9248
	ds_read_b128 v[114:117], v215 offset:13824
	ds_read_b128 v[200:203], v215 offset:13856
	v_max3_f32 v0, v240, v128, v129
	v_max3_f32 v14, v240, v130, v131
	s_nop 0
	v_max3_f32 v0, v0, v80, v81
	v_max3_f32 v14, v14, v82, v83
	s_waitcnt lgkmcnt(3)
	v_mfma_f32_32x32x16_bf16 v[144:159], v[96:99], v[184:187], v[160:175]
	ds_read_b128 v[192:195], v215 offset:9280
	ds_read_b128 v[118:121], v215 offset:13888
	v_max3_f32 v0, v0, v132, v133
	v_max3_f32 v14, v14, v134, v135
	s_nop 0
	v_max3_f32 v0, v0, v84, v85
	v_max3_f32 v14, v14, v86, v87
	s_waitcnt lgkmcnt(3)
	v_mfma_f32_32x32x16_bf16 v[96:111], v[114:117], v[184:187], v[160:175]
	v_max3_f32 v0, v0, v136, v137
	v_max3_f32 v14, v14, v138, v139
	s_nop 0
	v_max3_f32 v0, v0, v88, v89
	v_max3_f32 v14, v14, v90, v91
	v_mfma_f32_32x32x16_bf16 v[144:159], v[196:199], v[176:179], v[144:159]
	ds_read_b128 v[122:125], v215 offset:9312
	ds_read_b128 v[114:117], v215 offset:13920
	v_max3_f32 v0, v0, v140, v141
	v_max3_f32 v14, v14, v142, v143
	s_nop 0
	v_max3_f32 v0, v0, v92, v93
	v_max3_f32 v14, v14, v94, v95
	s_waitcnt lgkmcnt(4)
	v_mfma_f32_32x32x16_bf16 v[96:111], v[200:203], v[176:179], v[96:111]
	v_max_f32_e32 v0, v0, v14
	s_nop 0
	v_mov_b32_e32 v14, v0
	s_nop 1
	v_permlane32_swap_b32_e32 v0, v14
	v_max_f32_e32 v0, v0, v14
	s_nop 0
	v_cmp_lt_f32_e32 vcc, s2, v0
	v_cmp_gt_f32_e64 s[0:1], s3, v0
	s_or_b64 vcc, vcc, s[0:1]
	v_cndmask_b32_e64 v14, 0, 1, vcc
	v_cmp_ne_u32_e64 s[48:49], 0, v14
	s_cmp_lg_u64 s[48:49], 0
	s_cselect_b64 s[14:15], -1, 0
	s_cbranch_vccz .LBB0_977
	v_cmp_lt_f32_e32 vcc, 0, v0
	s_or_b64 vcc, vcc, s[0:1]
	s_nop 0
	v_cndmask_b32_e32 v0, 0, v0, vcc
	v_exp_f32_e64 v14, -v0
	v_pk_add_f32 v[128:129], v[128:129], v[0:1] op_sel_hi:[1,0] neg_lo:[0,1] neg_hi:[0,1]
	v_pk_add_f32 v[130:131], v[130:131], v[0:1] op_sel_hi:[1,0] neg_lo:[0,1] neg_hi:[0,1]
	v_pk_add_f32 v[132:133], v[132:133], v[0:1] op_sel_hi:[1,0] neg_lo:[0,1] neg_hi:[0,1]
	v_pk_add_f32 v[134:135], v[134:135], v[0:1] op_sel_hi:[1,0] neg_lo:[0,1] neg_hi:[0,1]
	v_pk_add_f32 v[136:137], v[136:137], v[0:1] op_sel_hi:[1,0] neg_lo:[0,1] neg_hi:[0,1]
	v_pk_add_f32 v[138:139], v[138:139], v[0:1] op_sel_hi:[1,0] neg_lo:[0,1] neg_hi:[0,1]
	v_pk_add_f32 v[140:141], v[140:141], v[0:1] op_sel_hi:[1,0] neg_lo:[0,1] neg_hi:[0,1]
	v_pk_add_f32 v[142:143], v[142:143], v[0:1] op_sel_hi:[1,0] neg_lo:[0,1] neg_hi:[0,1]
	v_sub_f32_e32 v95, v95, v0
	v_sub_f32_e32 v94, v94, v0
	v_sub_f32_e32 v93, v93, v0
	v_sub_f32_e32 v92, v92, v0
	v_sub_f32_e32 v91, v91, v0
	v_sub_f32_e32 v90, v90, v0
	v_sub_f32_e32 v89, v89, v0
	v_sub_f32_e32 v88, v88, v0
	v_sub_f32_e32 v87, v87, v0
	v_sub_f32_e32 v86, v86, v0
	v_sub_f32_e32 v85, v85, v0
	v_sub_f32_e32 v84, v84, v0
	v_sub_f32_e32 v83, v83, v0
	v_sub_f32_e32 v82, v82, v0
	v_sub_f32_e32 v81, v81, v0
	v_sub_f32_e32 v80, v80, v0
	v_add_f32_e32 v217, v217, v0
	s_branch .LBB0_978

.Lnegc_keep_5:
	s_min_u32 s1, s17, 28
	s_add_i32 s1, s1, 3
	v_mul_u32_u24_e32 v0, s1, v206
	s_min_u32 s0, s0, 31
	v_lshl_add_u64 v[2:3], v[208:209], 0, v[0:1]
	s_mul_i32 s40, s0, 0x108000
	global_load_dwordx4 v[10:13], v[2:3], off
	v_lshl_add_u64 v[2:3], v[210:211], 0, s[40:41]
	v_add_co_u32_e32 v6, vcc, s93, v2
	v_max3_f32 v0, v240, v144, v145
	v_max3_f32 v84, v240, v146, v147
	s_nop 1
	v_addc_co_u32_e32 v7, vcc, 0, v3, vcc
	global_load_dwordx4 v[2:5], v[2:3], off
	s_nop 0
	global_load_dwordx4 v[6:9], v[6:7], off
	ds_read_b128 v[80:83], v215
	ds_read_b128 v[196:199], v215 offset:32
	ds_read_b128 v[116:119], v215 offset:4608
	ds_read_b128 v[200:203], v215 offset:4640
	v_max3_f32 v0, v0, v96, v97
	v_max3_f32 v84, v84, v98, v99
	s_waitcnt lgkmcnt(3)
	v_mfma_f32_32x32x16_bf16 v[128:143], v[80:83], v[184:187], v[160:175]
	ds_read_b128 v[192:195], v215 offset:64
	ds_read_b128 v[120:123], v215 offset:4672
	v_max3_f32 v0, v0, v148, v149
	v_max3_f32 v84, v84, v150, v151
	s_nop 0
	v_max3_f32 v0, v0, v100, v101
	v_max3_f32 v84, v84, v102, v103
	s_nop 0
	v_max3_f32 v80, v84, v154, v155
	v_max3_f32 v0, v0, v152, v153
	s_nop 0
	v_max3_f32 v112, v80, v106, v107
	s_waitcnt lgkmcnt(3)
	v_mfma_f32_32x32x16_bf16 v[80:95], v[116:119], v[184:187], v[160:175]
	v_max3_f32 v0, v0, v104, v105
	v_mfma_f32_32x32x16_bf16 v[128:143], v[196:199], v[176:179], v[128:143]
	ds_read_b128 v[124:127], v215 offset:96
	ds_read_b128 v[116:119], v215 offset:4704
	v_max3_f32 v0, v0, v156, v157
	v_max3_f32 v112, v112, v158, v159
	s_nop 0
	v_max3_f32 v0, v0, v108, v109
	v_max3_f32 v112, v112, v110, v111
	s_waitcnt lgkmcnt(4)
	v_mfma_f32_32x32x16_bf16 v[80:95], v[200:203], v[176:179], v[80:95]
	v_max_f32_e32 v0, v0, v112
	s_nop 0
	v_mov_b32_e32 v112, v0
	s_nop 1
	v_permlane32_swap_b32_e32 v0, v112
	v_max_f32_e32 v0, v0, v112
	s_nop 0
	v_cmp_lt_f32_e32 vcc, s2, v0
	v_cmp_gt_f32_e64 s[0:1], s3, v0
	s_or_b64 vcc, vcc, s[0:1]
	v_cndmask_b32_e64 v112, 0, 1, vcc
	v_cmp_ne_u32_e64 s[48:49], 0, v112
	s_cmp_lg_u64 s[48:49], 0
	s_cselect_b64 s[14:15], -1, 0
	s_cbranch_vccz .LBB0_994
	v_cmp_lt_f32_e32 vcc, 0, v0
	s_or_b64 vcc, vcc, s[0:1]
	s_nop 0
	v_cndmask_b32_e32 v0, 0, v0, vcc
	v_exp_f32_e64 v112, -v0
	v_pk_add_f32 v[144:145], v[144:145], v[0:1] op_sel_hi:[1,0] neg_lo:[0,1] neg_hi:[0,1]
	v_pk_add_f32 v[146:147], v[146:147], v[0:1] op_sel_hi:[1,0] neg_lo:[0,1] neg_hi:[0,1]
	v_pk_add_f32 v[148:149], v[148:149], v[0:1] op_sel_hi:[1,0] neg_lo:[0,1] neg_hi:[0,1]
	v_pk_add_f32 v[150:151], v[150:151], v[0:1] op_sel_hi:[1,0] neg_lo:[0,1] neg_hi:[0,1]
	v_pk_add_f32 v[152:153], v[152:153], v[0:1] op_sel_hi:[1,0] neg_lo:[0,1] neg_hi:[0,1]
	v_pk_add_f32 v[154:155], v[154:155], v[0:1] op_sel_hi:[1,0] neg_lo:[0,1] neg_hi:[0,1]
	v_pk_add_f32 v[156:157], v[156:157], v[0:1] op_sel_hi:[1,0] neg_lo:[0,1] neg_hi:[0,1]
	v_pk_add_f32 v[158:159], v[158:159], v[0:1] op_sel_hi:[1,0] neg_lo:[0,1] neg_hi:[0,1]
	v_sub_f32_e32 v111, v111, v0
	v_sub_f32_e32 v110, v110, v0
	v_sub_f32_e32 v109, v109, v0
	v_sub_f32_e32 v108, v108, v0
	v_sub_f32_e32 v107, v107, v0
	v_sub_f32_e32 v106, v106, v0
	v_sub_f32_e32 v105, v105, v0
	v_sub_f32_e32 v104, v104, v0
	v_sub_f32_e32 v103, v103, v0
	v_sub_f32_e32 v102, v102, v0
	v_sub_f32_e32 v101, v101, v0
	v_sub_f32_e32 v100, v100, v0
	v_sub_f32_e32 v99, v99, v0
	v_sub_f32_e32 v98, v98, v0
	v_sub_f32_e32 v97, v97, v0
	v_sub_f32_e32 v96, v96, v0
	v_add_f32_e32 v217, v217, v0
	s_branch .LBB0_995
